# v87 plus DPP / permlane butterfly reductions in the F loop only
# speedup vs baseline: 1.0038x; 1.0038x over previous
.LBB0_1218:
	v_pk_add_f32 v[2:3], v[58:59], v[68:69]
	v_pk_add_f32 v[4:5], v[60:61], v[66:67]
	v_pk_add_f32 v[6:7], v[64:65], v[56:57]
	v_pk_add_f32 v[2:3], v[2:3], v[4:5]
	v_add_f32_e32 v14, v20, v21
	v_add_f32_e32 v18, v22, v23
	v_and_b32_e32 v26, 64, v249
	v_pk_add_f32 v[4:5], v[6:7], v[6:7] op_sel:[0,1] op_sel_hi:[1,0]
	v_add_f32_e32 v2, 0, v2
	v_add_f32_e32 v28, v36, v37
	v_add_f32_e32 v32, v40, v41
	v_pk_add_f32 v[34:35], v[14:15], v[18:19]
	v_add_u32_e32 v14, 64, v26
	v_mov_b32_e32 v5, v31
	v_add_f32_e32 v26, v2, v3
	v_pk_add_f32 v[6:7], v[28:29], v[32:33]
	v_pk_add_f32 v[2:3], v[26:27], v[4:5]
	v_pk_add_f32 v[8:9], v[62:63], v[24:25]
	v_pk_add_f32 v[2:3], v[2:3], v[6:7]
	v_pk_add_f32 v[8:9], v[8:9], v[8:9] op_sel:[0,1] op_sel_hi:[1,0]
	v_pk_add_f32 v[2:3], v[2:3], v[2:3] op_sel:[0,1] op_sel_hi:[1,0]
	v_xor_b32_e32 v30, 1, v249
	v_mov_b32_e32 v9, v17
	v_mov_b32_e32 v3, v16
	v_cmp_lt_i32_e32 vcc, v30, v14
	v_pk_add_f32 v[2:3], v[2:3], v[8:9]
	v_xor_b32_e32 v38, 2, v249
	v_cndmask_b32_e32 v18, v249, v30, vcc
	v_pk_add_f32 v[2:3], v[2:3], v[34:35]
	v_lshlrev_b32_e32 v82, 2, v18
	v_add_f32_e32 v26, v2, v3
	s_nop 1
	v_mov_b32_dpp v84, v26 quad_perm:[1,0,3,2] row_mask:0xf bank_mask:0xf
	v_cmp_lt_i32_e32 vcc, v38, v14
	v_xor_b32_e32 v39, 4, v249
	v_xor_b32_e32 v42, 8, v249
	v_cndmask_b32_e32 v28, v249, v38, vcc
	v_lshlrev_b32_e32 v32, 2, v28
	s_waitcnt lgkmcnt(0)
	v_add_f32_e32 v26, v26, v84
	s_nop 1
	v_mov_b32_dpp v84, v26 quad_perm:[2,3,0,1] row_mask:0xf bank_mask:0xf
	v_cmp_lt_i32_e32 vcc, v39, v14
	v_xor_b32_e32 v43, 16, v249
	s_add_i32 s28, s8, s60
	v_cndmask_b32_e32 v30, v249, v39, vcc
	v_lshlrev_b32_e32 v30, 2, v30
	s_waitcnt lgkmcnt(0)
	v_add_f32_e32 v26, v26, v84
	s_nop 1
	v_mov_b32_dpp v84, v26 row_half_mirror row_mask:0xf bank_mask:0xf
	v_cmp_lt_i32_e32 vcc, v42, v14
	s_cmpk_lt_i32 s28, 0x2000
	v_xor_b32_e32 v44, 32, v249
	v_cndmask_b32_e32 v38, v249, v42, vcc
	v_lshlrev_b32_e32 v28, 2, v38
	s_waitcnt lgkmcnt(0)
	v_add_f32_e32 v26, v26, v84
	s_nop 1
	v_mov_b32_dpp v84, v26 row_mirror row_mask:0xf bank_mask:0xf
	v_cmp_lt_i32_e32 vcc, v43, v14
	s_cselect_b32 s8, s28, s8
	s_ashr_i32 s9, s8, 31
	v_cndmask_b32_e32 v39, v249, v43, vcc
	v_lshlrev_b32_e32 v18, 2, v39
	s_waitcnt lgkmcnt(0)
	v_add_f32_e32 v26, v26, v84
	v_mov_b32_e32 v84, v26
	v_mov_b32_e32 v107, v26
	s_nop 1
	v_permlane16_swap_b32_e32 v84, v107
	v_cmp_lt_i32_e32 vcc, v44, v14
	s_lshl_b64 s[8:9], s[8:9], 12
	s_add_u32 s30, s14, s20
	v_cndmask_b32_e32 v14, v249, v44, vcc
	v_lshlrev_b32_e32 v14, 2, v14
	s_waitcnt lgkmcnt(0)
	s_nop 1
	v_add_f32_e32 v26, v84, v107
	v_mov_b32_e32 v70, v1
	v_lshl_add_u64 v[4:5], v[12:13], 0, s[8:9]
	s_addc_u32 s31, s15, s21
	v_mov_b32_e32 v84, v26
	v_mov_b32_e32 v107, v26
	s_nop 1
	v_permlane32_swap_b32_e32 v84, v107
	global_load_dwordx2 v[54:55], v[4:5], off
	global_load_dwordx2 v[52:53], v[4:5], off offset:512
	global_load_dwordx2 v[50:51], v[4:5], off offset:1024
	global_load_dwordx2 v[48:49], v[4:5], off offset:1536
	global_load_dwordx2 v[46:47], v[4:5], off offset:2048
	global_load_dwordx2 v[44:45], v[4:5], off offset:2560
	global_load_dwordx2 v[42:43], v[4:5], off offset:3072
	global_load_dwordx2 v[38:39], v[4:5], off offset:3584
	s_add_u32 s8, s14, s18
	v_lshlrev_b32_e32 v4, 2, v70
	s_addc_u32 s9, s15, s19
	v_ashrrev_i32_e32 v5, 31, v4
	v_lshlrev_b64 v[6:7], 2, v[4:5]
	v_lshl_add_u64 v[4:5], v[4:5], 1, s[8:9]
	v_lshl_add_u64 v[76:77], s[16:17], 0, v[6:7]
	v_add_co_u32_e32 v34, vcc, s61, v4
	v_lshl_add_u64 v[74:75], s[10:11], 0, v[6:7]
	v_lshl_add_u64 v[78:79], s[30:31], 0, v[6:7]
	v_lshl_add_u64 v[72:73], s[24:25], 0, v[6:7]
	v_lshl_add_u64 v[70:71], s[22:23], 0, v[6:7]
	v_addc_co_u32_e32 v35, vcc, 0, v5, vcc
	s_nop 1
	v_mov_b64_e32 v[2:3], v[180:181]
	v_mov_b64_e32 v[4:5], v[182:183]
	s_nop 1
	v_mov_b64_e32 v[6:7], v[212:213]
	v_mov_b64_e32 v[8:9], v[214:215]
	s_waitcnt lgkmcnt(0)
	s_nop 1
	v_add_f32_e32 v26, v84, v107
	v_fmac_f32_e32 v66, 0xba000000, v26
	v_fmac_f32_e32 v68, 0xba000000, v26
	v_fmac_f32_e32 v67, 0xba000000, v26
	v_fmac_f32_e32 v69, 0xba000000, v26
	v_fmac_f32_e32 v64, 0xba000000, v26
	v_fmac_f32_e32 v57, 0xba000000, v26
	v_fmac_f32_e32 v65, 0xba000000, v26
	v_fmac_f32_e32 v60, 0xba000000, v26
	v_fmac_f32_e32 v58, 0xba000000, v26
	v_fmac_f32_e32 v61, 0xba000000, v26
	v_fmac_f32_e32 v59, 0xba000000, v26
	v_fmac_f32_e32 v56, 0xba000000, v26
	v_mov_b32_e32 v85, v69
	v_mov_b32_e32 v87, v68
	v_pk_mul_f32 v[68:69], v[68:69], v[68:69]
	v_mov_b32_e32 v89, v67
	v_mov_b32_e32 v91, v66
	v_pk_mul_f32 v[66:67], v[66:67], v[66:67]
	v_mov_b32_e32 v92, v65
	v_mov_b32_e32 v93, v57
	v_mov_b32_e32 v57, v64
	v_mov_b32_e32 v84, v59
	v_mov_b32_e32 v86, v58
	v_mov_b32_e32 v88, v61
	v_mov_b32_e32 v90, v60
	v_pk_fma_f32 v[58:59], v[58:59], v[58:59], v[68:69]
	v_pk_fma_f32 v[60:61], v[60:61], v[60:61], v[66:67]
	v_pk_mul_f32 v[66:67], v[92:93], v[92:93]
	v_pk_mul_f32 v[68:69], v[56:57], v[56:57]
	v_fmac_f32_e32 v36, 0xba000000, v26
	v_fmac_f32_e32 v40, 0xba000000, v26
	v_pk_add_f32 v[58:59], v[58:59], v[60:61]
	v_pk_mov_b32 v[60:61], v[68:69], v[66:67] op_sel:[1,0]
	v_mov_b32_e32 v69, v67
	v_fmac_f32_e32 v37, 0xba000000, v26
	v_fmac_f32_e32 v41, 0xba000000, v26
	v_fmac_f32_e32 v33, 0xba000000, v26
	v_fmac_f32_e32 v29, 0xba000000, v26
	v_fmac_f32_e32 v31, 0xba000000, v26
	v_fmac_f32_e32 v27, 0xba000000, v26
	v_fmac_f32_e32 v62, 0xba000000, v26
	v_fmac_f32_e32 v24, 0xba000000, v26
	v_fmac_f32_e32 v25, 0xba000000, v26
	v_fmac_f32_e32 v63, 0xba000000, v26
	v_fmac_f32_e32 v21, 0xba000000, v26
	v_fmac_f32_e32 v20, 0xba000000, v26
	v_fmac_f32_e32 v23, 0xba000000, v26
	v_fmac_f32_e32 v22, 0xba000000, v26
	v_fmac_f32_e32 v19, 0xba000000, v26
	v_fmac_f32_e32 v15, 0xba000000, v26
	v_fmac_f32_e32 v17, 0xba000000, v26
	v_fmac_f32_e32 v16, 0xba000000, v26
	v_mul_f32_e32 v26, v36, v36
	v_mul_f32_e32 v94, v40, v40
	v_pk_add_f32 v[60:61], v[60:61], v[68:69]
	v_mov_b32_e32 v64, v63
	v_mov_b32_e32 v65, v25
	v_mov_b32_e32 v25, v62
	v_pk_fma_f32 v[98:99], v[36:37], v[36:37], v[26:27] op_sel_hi:[1,1,0]
	v_pk_fma_f32 v[94:95], v[40:41], v[40:41], v[94:95] op_sel_hi:[1,1,0]
	v_pk_add_f32 v[58:59], v[58:59], v[58:59] op_sel_hi:[0,1]
	v_pk_add_f32 v[60:61], v[60:61], v[60:61] op_sel_hi:[0,1]
	v_pk_mul_f32 v[100:101], v[64:65], v[64:65]
	v_pk_mul_f32 v[102:103], v[24:25], v[24:25]
	v_mul_f32_e32 v98, v27, v27
	v_mul_f32_e32 v94, v31, v31
	v_mul_f32_e32 v58, v33, v33
	v_mul_f32_e32 v60, v29, v29
	v_pk_mov_b32 v[66:67], v[102:103], v[100:101] op_sel:[1,0]
	v_mov_b32_e32 v103, v101
	v_pk_add_f32 v[68:69], v[98:99], v[94:95]
	v_pk_add_f32 v[58:59], v[60:61], v[58:59]
	v_mul_f32_e32 v62, v20, v20
	v_mul_f32_e32 v96, v22, v22
	v_pk_add_f32 v[66:67], v[66:67], v[102:103]
	v_pk_add_f32 v[58:59], v[68:69], v[58:59]
	v_pk_fma_f32 v[62:63], v[20:21], v[20:21], v[62:63] op_sel_hi:[1,1,0]
	v_pk_fma_f32 v[96:97], v[22:23], v[22:23], v[96:97] op_sel_hi:[1,1,0]
	v_pk_add_f32 v[66:67], v[66:67], v[66:67] op_sel_hi:[0,1]
	v_pk_add_f32 v[58:59], v[58:59], v[58:59] op_sel_hi:[0,1]
	v_mul_f32_e32 v62, v16, v16
	v_mul_f32_e32 v96, v17, v17
	v_mul_f32_e32 v66, v15, v15
	v_mul_f32_e32 v58, v19, v19
	v_pk_add_f32 v[62:63], v[62:63], v[96:97]
	v_pk_add_f32 v[58:59], v[66:67], v[58:59]
	s_mov_b32 s8, 0x21b1e000
	v_pk_add_f32 v[58:59], v[62:63], v[58:59]
	v_add_co_u32_e32 v80, vcc, s8, v78
	v_add_f32_e32 v26, v58, v59
	s_nop 1
	v_mov_b32_dpp v58, v26 quad_perm:[1,0,3,2] row_mask:0xf bank_mask:0xf
	v_addc_co_u32_e32 v81, vcc, 0, v79, vcc
	v_add_co_u32_e32 v78, vcc, s70, v78
	s_waitcnt lgkmcnt(0)
	v_add_f32_e32 v26, v26, v58
	s_nop 1
	v_mov_b32_dpp v32, v26 quad_perm:[2,3,0,1] row_mask:0xf bank_mask:0xf
	v_addc_co_u32_e32 v79, vcc, 0, v79, vcc
	s_add_u32 s20, s20, s36
	s_addc_u32 s21, s21, s37
	s_waitcnt lgkmcnt(0)
	v_add_f32_e32 v26, v26, v32
	s_nop 1
	v_mov_b32_dpp v30, v26 row_half_mirror row_mask:0xf bank_mask:0xf
	s_add_u32 s18, s18, s38
	s_addc_u32 s19, s19, s39
	s_cmpk_gt_i32 s28, 0x1fff
	s_waitcnt vmcnt(7)
	v_and_b32_e32 v68, 0xffff0000, v54
	s_waitcnt lgkmcnt(0)
	v_add_f32_e32 v26, v26, v30
	s_nop 1
	v_mov_b32_dpp v28, v26 row_mirror row_mask:0xf bank_mask:0xf
	s_waitcnt vmcnt(6)
	v_and_b32_e32 v69, 0xffff0000, v52
	s_waitcnt lgkmcnt(0)
	v_add_f32_e32 v26, v26, v28
	v_mov_b32_e32 v18, v26
	v_mov_b32_e32 v107, v26
	s_nop 1
	v_permlane16_swap_b32_e32 v18, v107
	s_waitcnt lgkmcnt(0)
	s_nop 1
	v_add_f32_e32 v18, v18, v107
	v_mov_b32_e32 v14, v18
	v_mov_b32_e32 v107, v18
	s_nop 1
	v_permlane32_swap_b32_e32 v14, v107
	s_waitcnt lgkmcnt(0)
	s_nop 1
	v_add_f32_e32 v14, v14, v107
	v_fmamk_f32 v14, v14, 0x3a000000, v250
	v_mul_f32_e32 v18, 0x4f800000, v14
	v_cmp_gt_f32_e32 vcc, s96, v14
	s_nop 1
	v_cndmask_b32_e32 v14, v14, v18, vcc
	v_sqrt_f32_e32 v18, v14
	s_nop 0
	v_add_u32_e32 v26, -1, v18
	v_add_u32_e32 v28, 1, v18
	v_fma_f32 v30, -v26, v18, v14
	v_fma_f32 v32, -v28, v18, v14
	v_cmp_ge_f32_e64 s[8:9], 0, v30
	s_nop 1
	v_cndmask_b32_e64 v18, v18, v26, s[8:9]
	v_cmp_lt_f32_e64 s[8:9], 0, v32
	s_nop 1
	v_cndmask_b32_e64 v18, v18, v28, s[8:9]
	v_mul_f32_e32 v26, 0x37800000, v18
	v_cndmask_b32_e32 v18, v18, v26, vcc
	v_cmp_class_f32_e32 vcc, v14, v251
	s_nop 1
	v_cndmask_b32_e32 v14, v18, v14, vcc
	v_div_scale_f32 v18, s[8:9], v14, v14, 1.0
	v_rcp_f32_e32 v28, v18
	v_div_scale_f32 v26, vcc, 1.0, v14, 1.0
	s_mov_b32 s8, s28
	v_fma_f32 v30, -v18, v28, 1.0
	v_fmac_f32_e32 v28, v30, v28
	v_mul_f32_e32 v30, v26, v28
	v_fma_f32 v32, -v18, v30, v26
	v_fmac_f32_e32 v30, v32, v28
	v_fma_f32 v18, -v18, v30, v26
	v_div_fmas_f32 v18, v18, v28, v30
	v_div_fixup_f32 v14, v18, v14, 1.0
	v_pk_mul_f32 v[58:59], v[86:87], v[14:15] op_sel_hi:[1,0]
	v_pk_mul_f32 v[60:61], v[90:91], v[14:15] op_sel_hi:[1,0]
	s_waitcnt vmcnt(0)
	v_pk_fma_f32 v[2:3], v[2:3], v[58:59], v[6:7]
	v_pk_fma_f32 v[4:5], v[4:5], v[60:61], v[8:9]
	global_store_dwordx4 v[78:79], v[2:5], off offset:-4096
	ds_read_b128 v[6:9], v144
	ds_read_b128 v[58:61], v144 offset:8192
	v_pk_mul_f32 v[62:63], v[88:89], v[14:15] op_sel_hi:[1,0]
	v_pk_mul_f32 v[66:67], v[84:85], v[14:15] op_sel_hi:[1,0]
	v_pk_mul_f32 v[56:57], v[56:57], v[14:15] op_sel_hi:[1,0]
	v_pk_mul_f32 v[40:41], v[40:41], v[14:15] op_sel_hi:[1,0]
	v_pk_mul_f32 v[36:37], v[36:37], v[14:15] op_sel_hi:[1,0]
	v_mov_b32_e32 v32, v29
	v_mov_b32_e32 v30, v27
	v_pk_mul_f32 v[26:27], v[32:33], v[14:15] op_sel_hi:[1,0]
	v_pk_mul_f32 v[28:29], v[30:31], v[14:15] op_sel_hi:[1,0]
	v_pk_mul_f32 v[24:25], v[24:25], v[14:15] op_sel_hi:[1,0]
	v_pk_mul_f32 v[22:23], v[22:23], v[14:15] op_sel_hi:[1,0]
	v_pk_mul_f32 v[20:21], v[20:21], v[14:15] op_sel_hi:[1,0]
	v_mov_b32_e32 v18, v15
	v_pk_mul_f32 v[18:19], v[18:19], v[14:15] op_sel_hi:[1,0]
	v_lshlrev_b32_e32 v30, 16, v49
	v_and_b32_e32 v32, 0xffff0000, v46
	v_and_b32_e32 v33, 0xffff0000, v47
	v_mov_b32_e32 v31, v32
	s_waitcnt lgkmcnt(1)
	v_pk_add_f32 v[8:9], v[8:9], 1.0 op_sel_hi:[1,0]
	v_pk_add_f32 v[6:7], v[6:7], 1.0 op_sel_hi:[1,0]
	s_waitcnt lgkmcnt(0)
	v_pk_fma_f32 v[4:5], v[8:9], v[4:5], v[60:61]
	v_pk_fma_f32 v[2:3], v[6:7], v[2:3], v[58:59]
	v_cvt_pk_bf16_f32 v2, v2, v3
	v_cvt_pk_bf16_f32 v3, v4, v5
	global_store_dwordx2 v[34:35], v[2:3], off
	s_nop 1
	v_mov_b64_e32 v[2:3], v[184:185]
	v_mov_b64_e32 v[4:5], v[186:187]
	s_nop 0
	s_nop 1
	v_mov_b64_e32 v[6:7], v[216:217]
	v_mov_b64_e32 v[8:9], v[218:219]
	s_waitcnt vmcnt(0)
	v_pk_fma_f32 v[2:3], v[2:3], v[66:67], v[6:7]
	v_pk_fma_f32 v[4:5], v[4:5], v[62:63], v[8:9]
	global_store_dwordx4 v[80:81], v[2:5], off offset:1024
	ds_read_b128 v[6:9], v144 offset:1024
	ds_read_b128 v[58:61], v144 offset:9216
	v_and_b32_e32 v62, 0xffff0000, v44
	v_lshlrev_b32_e32 v63, 16, v45
	v_and_b32_e32 v66, 0xffff0000, v55
	v_and_b32_e32 v67, 0xffff0000, v53
	s_waitcnt lgkmcnt(1)
	v_pk_add_f32 v[8:9], v[8:9], 1.0 op_sel_hi:[1,0]
	v_pk_add_f32 v[6:7], v[6:7], 1.0 op_sel_hi:[1,0]
	s_waitcnt lgkmcnt(0)
	v_pk_fma_f32 v[4:5], v[8:9], v[4:5], v[60:61]
	v_pk_fma_f32 v[2:3], v[6:7], v[2:3], v[58:59]
	v_cvt_pk_bf16_f32 v2, v2, v3
	v_cvt_pk_bf16_f32 v3, v4, v5
	global_store_dwordx2 v[34:35], v[2:3], off offset:512
	s_nop 1
	v_mov_b64_e32 v[2:3], v[188:189]
	v_mov_b64_e32 v[4:5], v[190:191]
	s_nop 0
	s_nop 1
	v_mov_b64_e32 v[6:7], v[220:221]
	v_mov_b64_e32 v[8:9], v[222:223]
	v_pk_mul_f32 v[58:59], v[92:93], v[14:15] op_sel_hi:[1,0]
	v_lshlrev_b32_e32 v60, 16, v55
	v_lshlrev_b32_e32 v61, 16, v53
	s_waitcnt vmcnt(0)
	v_pk_fma_f32 v[2:3], v[2:3], v[56:57], v[6:7]
	v_pk_fma_f32 v[4:5], v[4:5], v[58:59], v[8:9]
	global_store_dwordx4 v[80:81], v[2:5], off offset:2048
	ds_read_b128 v[6:9], v144 offset:2048
	ds_read_b128 v[56:59], v144 offset:10240
	s_waitcnt lgkmcnt(1)
	v_pk_add_f32 v[8:9], v[8:9], 1.0 op_sel_hi:[1,0]
	v_pk_add_f32 v[6:7], v[6:7], 1.0 op_sel_hi:[1,0]
	s_waitcnt lgkmcnt(0)
	v_pk_fma_f32 v[4:5], v[4:5], v[8:9], v[58:59]
	v_pk_fma_f32 v[2:3], v[2:3], v[6:7], v[56:57]
	v_cvt_pk_bf16_f32 v2, v2, v3
	v_cvt_pk_bf16_f32 v3, v4, v5
	global_store_dwordx2 v[34:35], v[2:3], off offset:1024
	s_nop 1
	v_mov_b64_e32 v[2:3], v[192:193]
	v_mov_b64_e32 v[4:5], v[194:195]
	s_nop 0
	s_nop 1
	v_mov_b64_e32 v[6:7], v[236:237]
	v_mov_b64_e32 v[8:9], v[238:239]
	s_waitcnt vmcnt(0)
	v_pk_fma_f32 v[2:3], v[36:37], v[2:3], v[6:7]
	v_pk_fma_f32 v[4:5], v[40:41], v[4:5], v[8:9]
	global_store_dwordx4 v[80:81], v[2:5], off offset:3072
	ds_read_b128 v[6:9], v144 offset:3072
	ds_read_b128 v[56:59], v144 offset:11264
	v_add_co_u32_e32 v36, vcc, s82, v76
	s_waitcnt lgkmcnt(1)
	v_pk_add_f32 v[8:9], v[8:9], 1.0 op_sel_hi:[1,0]
	v_pk_add_f32 v[6:7], v[6:7], 1.0 op_sel_hi:[1,0]
	s_waitcnt lgkmcnt(0)
	v_pk_fma_f32 v[4:5], v[4:5], v[8:9], v[58:59]
	v_pk_fma_f32 v[2:3], v[2:3], v[6:7], v[56:57]
	s_nop 0
	s_nop 0
	s_nop 0
	s_nop 0
	s_nop 0
	s_nop 0
	s_nop 0
	s_nop 0
	s_nop 0
	s_nop 0
	v_addc_co_u32_e32 v37, vcc, 0, v77, vcc
	v_cvt_pk_bf16_f32 v2, v2, v3
	v_cvt_pk_bf16_f32 v3, v4, v5
	v_add_co_u32_e32 v40, vcc, s82, v74
	global_store_dwordx2 v[34:35], v[2:3], off offset:1536
	s_nop 0
	v_addc_co_u32_e32 v41, vcc, 0, v75, vcc
	s_nop 1
	v_mov_b64_e32 v[2:3], v[196:197]
	v_mov_b64_e32 v[4:5], v[198:199]
	s_nop 1
	v_mov_b64_e32 v[6:7], v[240:241]
	v_mov_b64_e32 v[8:9], v[242:243]
	v_add_co_u32_e32 v56, vcc, s82, v72
	s_waitcnt vmcnt(0)
	v_pk_fma_f32 v[2:3], v[28:29], v[2:3], v[6:7]
	v_addc_co_u32_e32 v57, vcc, 0, v73, vcc
	v_pk_fma_f32 v[4:5], v[26:27], v[4:5], v[8:9]
	v_add_co_u32_e32 v58, vcc, s82, v70
	global_store_dwordx4 v[78:79], v[2:5], off
	s_nop 0
	v_addc_co_u32_e32 v59, vcc, 0, v71, vcc
	ds_read_b128 v[6:9], v144 offset:4096
	ds_read_b128 v[26:29], v144 offset:12288
	s_waitcnt lgkmcnt(1)
	v_pk_add_f32 v[8:9], v[8:9], 1.0 op_sel_hi:[1,0]
	v_pk_add_f32 v[6:7], v[6:7], 1.0 op_sel_hi:[1,0]
	s_waitcnt lgkmcnt(0)
	v_pk_fma_f32 v[4:5], v[4:5], v[8:9], v[28:29]
	v_pk_fma_f32 v[2:3], v[2:3], v[6:7], v[26:27]
	v_cvt_pk_bf16_f32 v2, v2, v3
	v_cvt_pk_bf16_f32 v3, v4, v5
	global_store_dwordx2 v[34:35], v[2:3], off offset:2048
	s_nop 1
	v_mov_b64_e32 v[2:3], v[200:201]
	v_mov_b64_e32 v[4:5], v[202:203]
	s_nop 0
	s_nop 1
	v_mov_b64_e32 v[6:7], v[128:129]
	v_mov_b64_e32 v[8:9], v[130:131]
	v_pk_mul_f32 v[26:27], v[64:65], v[14:15] op_sel_hi:[1,0]
	v_pk_mul_f32 v[14:15], v[16:17], v[14:15] op_sel_hi:[1,0]
	v_and_b32_e32 v28, 0xffff0000, v48
	v_lshlrev_b32_e32 v29, 16, v47
	v_lshlrev_b32_e32 v47, 16, v43
	v_and_b32_e32 v43, 0xffff0000, v43
	v_and_b32_e32 v64, 0xffff0000, v50
	v_lshlrev_b32_e32 v65, 16, v51
	s_waitcnt vmcnt(0)
	v_pk_fma_f32 v[2:3], v[24:25], v[2:3], v[6:7]
	v_pk_fma_f32 v[4:5], v[26:27], v[4:5], v[8:9]
	global_store_dwordx4 v[78:79], v[2:5], off offset:1024
	ds_read_b128 v[6:9], v144 offset:5120
	ds_read_b128 v[24:27], v144 offset:13312
	s_waitcnt lgkmcnt(1)
	v_pk_add_f32 v[8:9], v[8:9], 1.0 op_sel_hi:[1,0]
	v_pk_add_f32 v[6:7], v[6:7], 1.0 op_sel_hi:[1,0]
	s_waitcnt lgkmcnt(0)
	v_pk_fma_f32 v[4:5], v[4:5], v[8:9], v[26:27]
	v_pk_fma_f32 v[2:3], v[2:3], v[6:7], v[24:25]
	v_cvt_pk_bf16_f32 v2, v2, v3
	v_cvt_pk_bf16_f32 v3, v4, v5
	global_store_dwordx2 v[34:35], v[2:3], off offset:2560
	s_nop 1
	v_mov_b64_e32 v[2:3], v[204:205]
	v_mov_b64_e32 v[4:5], v[206:207]
	s_nop 0
	s_nop 1
	v_mov_b64_e32 v[6:7], v[132:133]
	v_mov_b64_e32 v[8:9], v[134:135]
	v_lshlrev_b32_e32 v26, 16, v48
	v_lshlrev_b32_e32 v27, 16, v46
	v_lshlrev_b32_e32 v46, 16, v44
	v_and_b32_e32 v44, 0xffff0000, v45
	v_lshlrev_b32_e32 v45, 16, v42
	v_and_b32_e32 v42, 0xffff0000, v42
	v_lshlrev_b32_e32 v48, 16, v38
	v_and_b32_e32 v38, 0xffff0000, v38
	v_mov_b32_e32 v24, v46
	v_mov_b32_e32 v25, v44
	v_mov_b32_e32 v16, v48
	v_mov_b32_e32 v17, v38
	s_waitcnt vmcnt(0)
	v_pk_fma_f32 v[2:3], v[20:21], v[2:3], v[6:7]
	v_pk_fma_f32 v[4:5], v[22:23], v[4:5], v[8:9]
	global_store_dwordx4 v[78:79], v[2:5], off offset:2048
	ds_read_b128 v[6:9], v144 offset:6144
	ds_read_b128 v[20:23], v144 offset:14336
	s_waitcnt lgkmcnt(1)
	v_pk_add_f32 v[8:9], v[8:9], 1.0 op_sel_hi:[1,0]
	v_pk_add_f32 v[6:7], v[6:7], 1.0 op_sel_hi:[1,0]
	s_waitcnt lgkmcnt(0)
	v_pk_fma_f32 v[4:5], v[4:5], v[8:9], v[22:23]
	v_pk_fma_f32 v[2:3], v[2:3], v[6:7], v[20:21]
	v_cvt_pk_bf16_f32 v2, v2, v3
	v_cvt_pk_bf16_f32 v3, v4, v5
	global_store_dwordx2 v[34:35], v[2:3], off offset:3072
	s_nop 1
	v_mov_b64_e32 v[2:3], v[208:209]
	v_mov_b64_e32 v[4:5], v[210:211]
	s_nop 0
	s_nop 1
	v_mov_b64_e32 v[6:7], v[140:141]
	v_mov_b64_e32 v[8:9], v[142:143]
	v_lshlrev_b32_e32 v40, 16, v39
	v_and_b32_e32 v39, 0xffff0000, v39
	v_and_b32_e32 v41, 0xffff0000, v49
	v_mov_b32_e32 v36, v26
	v_mov_b32_e32 v37, v28
	v_mov_b32_e32 v20, v45
	v_mov_b32_e32 v21, v42
	v_mov_b32_e32 v22, v47
	v_mov_b32_e32 v23, v43
	s_waitcnt vmcnt(0)
	v_pk_fma_f32 v[2:3], v[14:15], v[2:3], v[6:7]
	v_pk_fma_f32 v[4:5], v[18:19], v[4:5], v[8:9]
	global_store_dwordx4 v[78:79], v[2:5], off offset:3072
	ds_read_b128 v[6:9], v144 offset:7168
	ds_read_b128 v[70:73], v144 offset:15360
	v_lshlrev_b32_e32 v58, 16, v54
	v_lshlrev_b32_e32 v59, 16, v52
	v_lshlrev_b32_e32 v56, 16, v50
	v_and_b32_e32 v57, 0xffff0000, v51
	v_mov_b32_e32 v15, v40
	v_mov_b32_e32 v40, v30
	v_mov_b32_e32 v19, v39
	s_waitcnt lgkmcnt(1)
	v_pk_add_f32 v[8:9], v[8:9], 1.0 op_sel_hi:[1,0]
	v_pk_add_f32 v[6:7], v[6:7], 1.0 op_sel_hi:[1,0]
	s_waitcnt lgkmcnt(0)
	v_pk_fma_f32 v[4:5], v[4:5], v[8:9], v[72:73]
	v_pk_fma_f32 v[2:3], v[2:3], v[6:7], v[70:71]
	v_bfe_u32 v8, v4, 16, 1
	v_bfe_u32 v6, v2, 16, 1
	v_bfe_u32 v7, v3, 16, 1
	v_bfe_u32 v9, v5, 16, 1
	v_add3_u32 v2, v2, v6, s73
	v_add3_u32 v4, v4, v8, s73
	v_add3_u32 v3, v3, v7, s73
	v_add3_u32 v5, v5, v9, s73
	v_lshrrev_b32_e32 v2, 16, v2
	v_lshrrev_b32_e32 v4, 16, v4
	v_and_or_b32 v2, v3, s33, v2
	v_and_or_b32 v3, v5, s33, v4
	global_store_dwordx2 v[34:35], v[2:3], off offset:3584
	s_cbranch_scc0 .LBB0_1218
